# stack: v31 + cmp1 bias preload + softmax v_pk_fma_f32
# baseline (speedup 1.0000x reference)
; #define K_STEP(ks) { bf16x8 xa0, xa1, xa2, xa3, xb0, xb1; FR_LOAD(ks, x) FR_MMA(x) \
;                      if (wr) GL_STORE(ks) if (ld) GL_LOADA(ks, kt + 2) }
; template <bool AF32, class AR>
; DI void gemm_loop(f32x16 (&acc)[4][2], GR& R, const AR& ar, const bf16_t* __restrict__ Bt, int ldb, int m0, int n0, int nk, bf16_t* lds, bool swp) {
;     ...
;   for (int kt = 0; kt < nk; ++kt) {
;     const bool wr = kt + 1 < nk, ld = kt + 2 < nk;
;     bf16_t* sA = lds + ((kt + 1) & 1) * LDS_TILE;
;     bf16_t* sB = lds + 2 * LDS_TILE + ((kt + 1) & 1) * LDS_TILE;
;     const bf16_t* cA = lds + (kt & 1) * LDS_TILE;
;     const bf16_t* cB = lds + 2 * LDS_TILE + (kt & 1) * LDS_TILE;
;     const bf16_t* pa = (swp ? cB : cA) + (wm * 128 + r) * 72 + 8 * h;
;     const bf16_t* pb = (swp ? cA : cB) + (wn * 64 + r) * 72 + 8 * h;
;     ...
;     K_STEP(0) K_STEP(1) K_STEP(2) K_STEP(3)
;     ...
;     __syncthreads();
;   }
.LBB0_1122:
	s_add_i32 s12, s2, 1
	s_bitcmp1_b32 s12, 0
	s_cselect_b32 s13, 0x9000, 0
	s_bitcmp1_b32 s2, 0
	s_cselect_b32 s14, 0x9000, 0
	v_add_u32_e32 v163, s14, v168
	v_add_u32_e32 v173, s14, v169
	ds_read_b128 v[174:177], v163
	ds_read_b128 v[178:181], v173
	ds_read_b128 v[182:185], v163 offset:4608
	ds_read_b128 v[186:189], v173 offset:4608
	s_waitcnt lgkmcnt(2)
	v_mfma_f32_32x32x16_bf16 v[112:127], v[174:177], v[178:181], v[112:127]
	v_add_u32_e32 v195, s13, v170
	v_add_u32_e32 v194, s13, v172
	s_cmp_lg_u32 s12, 30
	s_waitcnt lgkmcnt(0)
	v_mfma_f32_32x32x16_bf16 v[48:63], v[174:177], v[186:189], v[48:63]
	v_mfma_f32_32x32x16_bf16 v[96:111], v[182:185], v[178:181], v[96:111]
	v_mfma_f32_32x32x16_bf16 v[32:47], v[182:185], v[186:189], v[32:47]
	ds_read_b128 v[174:177], v163 offset:9216
	ds_read_b128 v[182:185], v163 offset:13824
	s_waitcnt vmcnt(7)
	ds_write_b128 v195, v[156:159]
	s_waitcnt vmcnt(6)
	ds_write_b128 v194, v[152:155]
	s_waitcnt lgkmcnt(3)
	v_mfma_f32_32x32x16_bf16 v[80:95], v[174:177], v[178:181], v[80:95]
	v_mfma_f32_32x32x16_bf16 v[16:31], v[174:177], v[186:189], v[16:31]
	s_waitcnt lgkmcnt(2)
	v_mfma_f32_32x32x16_bf16 v[64:79], v[182:185], v[178:181], v[64:79]
	ds_read_b128 v[152:155], v163 offset:32
	ds_read_b128 v[156:159], v173 offset:32
	ds_read_b128 v[174:177], v163 offset:4640
	ds_read_b128 v[178:181], v173 offset:4640
	s_waitcnt lgkmcnt(2)
	v_mfma_f32_32x32x16_bf16 v[112:127], v[152:155], v[156:159], v[112:127]
	s_waitcnt lgkmcnt(0)
	v_mfma_f32_32x32x16_bf16 v[48:63], v[152:155], v[178:181], v[48:63]
	v_mfma_f32_32x32x16_bf16 v[96:111], v[174:177], v[156:159], v[96:111]
	v_mfma_f32_32x32x16_bf16 v[32:47], v[174:177], v[178:181], v[32:47]
	ds_read_b128 v[152:155], v163 offset:9248
	ds_read_b128 v[174:177], v163 offset:13856
	s_waitcnt vmcnt(5)
	ds_write_b128 v195, v[144:147] offset:9216
	s_waitcnt vmcnt(4)
	ds_write_b128 v194, v[148:151] offset:9216
	v_mfma_f32_32x32x16_bf16 v[0:15], v[182:185], v[186:189], v[0:15]
	s_waitcnt lgkmcnt(3)
	v_mfma_f32_32x32x16_bf16 v[80:95], v[152:155], v[156:159], v[80:95]
	v_mfma_f32_32x32x16_bf16 v[16:31], v[152:155], v[178:181], v[16:31]
	s_waitcnt lgkmcnt(2)
	v_mfma_f32_32x32x16_bf16 v[64:79], v[174:177], v[156:159], v[64:79]
	ds_read_b128 v[144:147], v163 offset:64
	ds_read_b128 v[148:151], v173 offset:64
	ds_read_b128 v[152:155], v163 offset:4672
	ds_read_b128 v[156:159], v173 offset:4672
	s_waitcnt lgkmcnt(2)
	v_mfma_f32_32x32x16_bf16 v[112:127], v[144:147], v[148:151], v[112:127]
	s_waitcnt lgkmcnt(0)
	v_mfma_f32_32x32x16_bf16 v[48:63], v[144:147], v[156:159], v[48:63]
	v_mfma_f32_32x32x16_bf16 v[0:15], v[174:177], v[178:181], v[0:15]
	v_mfma_f32_32x32x16_bf16 v[96:111], v[152:155], v[148:151], v[96:111]
	v_mfma_f32_32x32x16_bf16 v[32:47], v[152:155], v[156:159], v[32:47]
	ds_read_b128 v[144:147], v163 offset:9280
	ds_read_b128 v[152:155], v163 offset:13888
	s_waitcnt vmcnt(3)
	ds_write_b128 v195, v[136:139] offset:18432
	s_waitcnt vmcnt(2)
	ds_write_b128 v194, v[140:143] offset:18432
	ds_read_b128 v[136:139], v163 offset:96
	ds_read_b128 v[174:177], v173 offset:96
	ds_read_b128 v[140:143], v163 offset:4704
	ds_read_b128 v[178:181], v173 offset:4704
	s_waitcnt lgkmcnt(7)
	v_mfma_f32_32x32x16_bf16 v[80:95], v[144:147], v[148:151], v[80:95]
	v_mfma_f32_32x32x16_bf16 v[16:31], v[144:147], v[156:159], v[16:31]
	v_add_u32_e32 v147, s2, v160
	v_add_co_u32_e32 v144, vcc, s27, v166
	v_add_u32_e32 v146, 0x202, v147
	s_nop 0
	v_addc_co_u32_e32 v145, vcc, -1, v167, vcc
	s_mov_b32 s2, s12
	s_waitcnt lgkmcnt(2)
	v_mfma_f32_32x32x16_bf16 v[112:127], v[136:139], v[174:177], v[112:127]
	s_waitcnt lgkmcnt(0)
	v_mfma_f32_32x32x16_bf16 v[48:63], v[136:139], v[178:181], v[48:63]
	v_add_u32_e32 v136, 2, v147
	v_add_u32_e32 v138, 0x102, v147
	v_ashrrev_i32_e32 v137, 31, v136
	v_ashrrev_i32_e32 v139, 31, v138
	v_mfma_f32_32x32x16_bf16 v[64:79], v[152:155], v[148:151], v[64:79]
	v_add_u32_e32 v150, 0x302, v147
	v_add_co_u32_e32 v148, vcc, s28, v166
	v_ashrrev_i32_e32 v147, 31, v146
	v_ashrrev_i32_e32 v151, 31, v150
	v_addc_co_u32_e32 v149, vcc, -1, v167, vcc
	v_mfma_f32_32x32x16_bf16 v[0:15], v[152:155], v[156:159], v[0:15]
	v_lshlrev_b64 v[152:153], 9, v[136:137]
	v_lshlrev_b64 v[154:155], 9, v[138:139]
	ds_read_b128 v[136:139], v163 offset:9312
	ds_read_b128 v[182:185], v163 offset:13920
	v_lshlrev_b64 v[146:147], 9, v[146:147]
	v_add_co_u32_e32 v186, vcc, s20, v166
	v_lshl_add_u64 v[188:189], v[164:165], 0, v[146:147]
	v_mfma_f32_32x32x16_bf16 v[96:111], v[140:143], v[174:177], v[96:111]
	v_addc_co_u32_e32 v187, vcc, 0, v167, vcc
	v_mfma_f32_32x32x16_bf16 v[32:47], v[140:143], v[178:181], v[32:47]
	v_lshlrev_b64 v[140:141], 9, v[150:151]
	v_lshl_add_u64 v[142:143], v[164:165], 0, v[152:153]
	v_lshl_add_u64 v[150:151], v[164:165], 0, v[154:155]
	v_lshl_add_u64 v[190:191], v[164:165], 0, v[140:141]
	global_load_dwordx4 v[156:159], v[142:143], off
	global_load_dwordx4 v[152:155], v[144:145], off
	s_waitcnt lgkmcnt(1)
	v_mfma_f32_32x32x16_bf16 v[80:95], v[136:139], v[174:177], v[80:95]
	v_mfma_f32_32x32x16_bf16 v[16:31], v[136:139], v[178:181], v[16:31]
	global_load_dwordx4 v[144:147], v[150:151], off
	s_nop 0
	global_load_dwordx4 v[148:151], v[148:149], off
	s_nop 0
	global_load_dwordx4 v[136:139], v[188:189], off
	global_load_dwordx4 v[140:143], v[166:167], off
	s_waitcnt vmcnt(7)
	ds_write_b128 v195, v[128:131] offset:27648
	s_waitcnt vmcnt(6)
	ds_write_b128 v194, v[132:135] offset:27648
	global_load_dwordx4 v[128:131], v[190:191], off
	global_load_dwordx4 v[132:135], v[186:187], off
	v_lshl_add_u64 v[166:167], v[166:167], 0, s[4:5]
	s_waitcnt lgkmcnt(0)
	s_barrier
; #define K_STEP(ks) { bf16x8 xa0, xa1, xa2, xa3, xb0, xb1; FR_LOAD(ks, x) FR_MMA(x) \
;                      if (wr) GL_STORE(ks) if (ld) GL_LOADA(ks, kt + 2) }
; template <bool AF32, class AR>
; DI void gemm_loop(f32x16 (&acc)[4][2], GR& R, const AR& ar, const bf16_t* __restrict__ Bt, int ldb, int m0, int n0, int nk, bf16_t* lds, bool swp) {
;     ...
;   for (int kt = 0; kt < nk; ++kt) {
;     const bool wr = kt + 1 < nk, ld = kt + 2 < nk;
;     bf16_t* sA = lds + ((kt + 1) & 1) * LDS_TILE;
;     bf16_t* sB = lds + 2 * LDS_TILE + ((kt + 1) & 1) * LDS_TILE;
;     const bf16_t* cA = lds + (kt & 1) * LDS_TILE;
;     const bf16_t* cB = lds + 2 * LDS_TILE + (kt & 1) * LDS_TILE;
;     const bf16_t* pa = (swp ? cB : cA) + (wm * 128 + r) * 72 + 8 * h;
;     const bf16_t* pb = (swp ? cA : cB) + (wn * 64 + r) * 72 + 8 * h;
;     ...
;     K_STEP(0) K_STEP(1) K_STEP(2) K_STEP(3)
;     ...
;     __syncthreads();
;   }
	v_mfma_f32_32x32x16_bf16 v[64:79], v[182:185], v[174:177], v[64:79]
	v_mfma_f32_32x32x16_bf16 v[0:15], v[182:185], v[178:181], v[0:15]
	s_cbranch_scc1 .LBB0_1122
	ds_read_b128 v[164:167], v168
	ds_read_b128 v[172:175], v168 offset:4608
	ds_read_b128 v[176:179], v168 offset:9216
	ds_read_b128 v[180:183], v168 offset:13824
	ds_read_b128 v[184:187], v169
	ds_read_b128 v[188:191], v169 offset:4608
	v_lshlrev_b32_e32 v160, 1, v171
	v_add3_u32 v160, v160, v162, s29
	s_waitcnt vmcnt(7)
	ds_write_b128 v170, v[156:159] offset:36864
	s_waitcnt vmcnt(6)
	ds_write_b128 v160, v[152:155]
	s_waitcnt lgkmcnt(3)
	v_mfma_f32_32x32x16_bf16 v[112:127], v[164:167], v[184:187], v[112:127]
	s_and_b64 s[10:11], s[10:11], exec
	s_cselect_b32 s2, s30, 0x1d000000
	s_add_u32 s10, s76, s2
	s_addc_u32 s11, s77, 0
	s_lshl_b32 s2, s33, 2
	s_and_b32 s12, s2, 0xffffff00
	s_ashr_i32 s13, s12, 31
	s_waitcnt lgkmcnt(2)
	v_mfma_f32_32x32x16_bf16 v[48:63], v[164:167], v[188:191], v[48:63]
	s_lshl_b64 s[12:13], s[12:13], 2
	s_add_u32 s12, s6, s12
	s_addc_u32 s13, s7, s13
	s_add_i32 s33, s33, s74
	s_add_i32 s16, s16, s17
	s_cmpk_lt_i32 s33, 0x80
	v_mfma_f32_32x32x16_bf16 v[32:47], v[172:175], v[188:191], v[32:47]
	v_mfma_f32_32x32x16_bf16 v[16:31], v[176:179], v[188:191], v[16:31]
	v_mfma_f32_32x32x16_bf16 v[0:15], v[180:183], v[188:191], v[0:15]
	v_mfma_f32_32x32x16_bf16 v[96:111], v[172:175], v[184:187], v[96:111]
	v_mfma_f32_32x32x16_bf16 v[80:95], v[176:179], v[184:187], v[80:95]
	v_mfma_f32_32x32x16_bf16 v[64:79], v[180:183], v[184:187], v[64:79]
	ds_read_b128 v[152:155], v168 offset:32
	ds_read_b128 v[156:159], v168 offset:4640
	ds_read_b128 v[162:165], v168 offset:9248
	ds_read_b128 v[172:175], v168 offset:13856
	ds_read_b128 v[176:179], v169 offset:32
	ds_read_b128 v[180:183], v169 offset:4640
	s_waitcnt vmcnt(5)
	ds_write_b128 v170, v[144:147] offset:46080
	s_waitcnt vmcnt(4)
	ds_write_b128 v160, v[148:151] offset:9216
	s_waitcnt lgkmcnt(2)
	v_mfma_f32_32x32x16_bf16 v[48:63], v[152:155], v[180:183], v[48:63]
	v_mfma_f32_32x32x16_bf16 v[32:47], v[156:159], v[180:183], v[32:47]
	v_mfma_f32_32x32x16_bf16 v[16:31], v[162:165], v[180:183], v[16:31]
	v_mfma_f32_32x32x16_bf16 v[0:15], v[172:175], v[180:183], v[0:15]
	v_mfma_f32_32x32x16_bf16 v[112:127], v[152:155], v[176:179], v[112:127]
	v_mfma_f32_32x32x16_bf16 v[96:111], v[156:159], v[176:179], v[96:111]
	v_mfma_f32_32x32x16_bf16 v[80:95], v[162:165], v[176:179], v[80:95]
	v_mfma_f32_32x32x16_bf16 v[64:79], v[172:175], v[176:179], v[64:79]
	ds_read_b128 v[144:147], v168 offset:64
	ds_read_b128 v[148:151], v168 offset:4672
	ds_read_b128 v[152:155], v168 offset:9280
	ds_read_b128 v[156:159], v168 offset:13888
	ds_read_b128 v[162:165], v169 offset:64
	ds_read_b128 v[172:175], v169 offset:4672
	s_waitcnt vmcnt(3)
	ds_write_b128 v170, v[136:139] offset:55296
	s_waitcnt vmcnt(2)
	ds_write_b128 v160, v[140:143] offset:18432
	s_waitcnt lgkmcnt(2)
	v_mfma_f32_32x32x16_bf16 v[48:63], v[144:147], v[172:175], v[48:63]
	v_mfma_f32_32x32x16_bf16 v[32:47], v[148:151], v[172:175], v[32:47]
	v_mfma_f32_32x32x16_bf16 v[16:31], v[152:155], v[172:175], v[16:31]
	v_mfma_f32_32x32x16_bf16 v[0:15], v[156:159], v[172:175], v[0:15]
	v_mfma_f32_32x32x16_bf16 v[112:127], v[144:147], v[162:165], v[112:127]
	v_mfma_f32_32x32x16_bf16 v[96:111], v[148:151], v[162:165], v[96:111]
	v_mfma_f32_32x32x16_bf16 v[80:95], v[152:155], v[162:165], v[80:95]
	v_mfma_f32_32x32x16_bf16 v[64:79], v[156:159], v[162:165], v[64:79]
	ds_read_b128 v[136:139], v168 offset:96
	ds_read_b128 v[140:143], v168 offset:4704
	ds_read_b128 v[144:147], v168 offset:9312
	ds_read_b128 v[148:151], v168 offset:13920
	ds_read_b128 v[152:155], v169 offset:96
	ds_read_b128 v[156:159], v169 offset:4704
	s_waitcnt vmcnt(1)
	ds_write_b128 v170, v[128:131] offset:64512
	s_waitcnt vmcnt(0)
	ds_write_b128 v160, v[132:135] offset:27648
	s_waitcnt lgkmcnt(0)
	s_barrier
	v_mfma_f32_32x32x16_bf16 v[48:63], v[136:139], v[156:159], v[48:63]
	v_mfma_f32_32x32x16_bf16 v[32:47], v[140:143], v[156:159], v[32:47]
	v_mfma_f32_32x32x16_bf16 v[16:31], v[144:147], v[156:159], v[16:31]
	v_mfma_f32_32x32x16_bf16 v[0:15], v[148:151], v[156:159], v[0:15]
	v_mfma_f32_32x32x16_bf16 v[112:127], v[136:139], v[152:155], v[112:127]
	v_mfma_f32_32x32x16_bf16 v[96:111], v[140:143], v[152:155], v[96:111]
	v_mfma_f32_32x32x16_bf16 v[80:95], v[144:147], v[152:155], v[80:95]
	v_mfma_f32_32x32x16_bf16 v[64:79], v[148:151], v[152:155], v[64:79]
	ds_read_b128 v[128:131], v168 offset:41472
	ds_read_b128 v[132:135], v168 offset:46080
	ds_read_b128 v[136:139], v168 offset:50688
	ds_read_b128 v[140:143], v169 offset:41472
	ds_read_b128 v[144:147], v169 offset:36864
	ds_read_b128 v[148:151], v169 offset:36896
	ds_read_b128 v[152:155], v168 offset:36864
	ds_read_b128 v[156:159], v168 offset:36896
	s_waitcnt lgkmcnt(1)
	v_mfma_f32_32x32x16_bf16 v[48:63], v[152:155], v[140:143], v[48:63]
	v_mfma_f32_32x32x16_bf16 v[32:47], v[128:131], v[140:143], v[32:47]
	v_mfma_f32_32x32x16_bf16 v[16:31], v[132:135], v[140:143], v[16:31]
	v_mfma_f32_32x32x16_bf16 v[0:15], v[136:139], v[140:143], v[0:15]
	v_mfma_f32_32x32x16_bf16 v[112:127], v[152:155], v[144:147], v[112:127]
	v_mfma_f32_32x32x16_bf16 v[96:111], v[128:131], v[144:147], v[96:111]
	v_mfma_f32_32x32x16_bf16 v[80:95], v[132:135], v[144:147], v[80:95]
	v_mfma_f32_32x32x16_bf16 v[64:79], v[136:139], v[144:147], v[64:79]
	ds_read_b128 v[128:131], v169 offset:41504
	ds_read_b128 v[132:135], v168 offset:50720
	ds_read_b128 v[136:139], v168 offset:46112
	ds_read_b128 v[140:143], v168 offset:41504
	s_waitcnt lgkmcnt(3)
	v_mfma_f32_32x32x16_bf16 v[48:63], v[156:159], v[128:131], v[48:63]
	s_waitcnt lgkmcnt(0)
; DI unsigned pack2(float a, float b) { f32x2_t v = {a, b}; bf16x2_t r = __builtin_convertvector(v, bf16x2_t); return __builtin_bit_cast(unsigned, r); }
; DI float bflo(unsigned u) { return __uint_as_float(u << 16); }
; DI float bfhi(unsigned u) { return __uint_as_float(u & 0xffff0000u); }
; DI float siluf_(float x) { return x * __builtin_amdgcn_rcpf(1.f + __expf(-x)); }
; DI void epi_seg(const f32x16 (&acc)[4][2], const Seg& sg0, const Seg& sg1, int m0, int n0, const float* rs, const float2* cs64, const float2* cs32, bf16_t* stg) {
;     ...
;       } else {
; #pragma unroll
;         for (int ch = 0; ch < 2; ++ch) {
;           float ss = 0.f;
; #pragma unroll
;           for (int i = 2 * ch; i < 2 * ch + 2; ++i)
; #pragma unroll
;             for (int q4 = 0; q4 < 4; ++q4) {
;               float v[4] = {acc[i][j][4 * q4] * sc, acc[i][j][4 * q4 + 1] * sc, acc[i][j][4 * q4 + 2] * sc, acc[i][j][4 * q4 + 3] * sc};
;               if (kind == K_SILU) {
;                 const f32x4 bv = *(const f32x4*)(sg.bias + lcw + i * 32 + 8 * q4 + 4 * h);
;                 v[0] = siluf_(v[0] + bv.x); v[1] = siluf_(v[1] + bv.y); v[2] = siluf_(v[2] + bv.z); v[3] = siluf_(v[3] + bv.w);
;               }
;               const uint2 pk = make_uint2(pack2(v[0], v[1]), pack2(v[2], v[3]));
;               *(uint2*)(srow + i * 32 + 8 * q4) = pk;
;               const float f0 = bflo(pk.x), f1 = bfhi(pk.x), f2 = bflo(pk.y), f3 = bfhi(pk.y);
;               ss += (f0 * f0 + f1 * f1) + (f2 * f2 + f3 * f3);
;             }
	v_mfma_f32_32x32x16_bf16 v[32:47], v[140:143], v[128:131], v[32:47]
	v_mfma_f32_32x32x16_bf16 v[16:31], v[136:139], v[128:131], v[16:31]
	v_mfma_f32_32x32x16_bf16 v[0:15], v[132:135], v[128:131], v[0:15]
	v_mfma_f32_32x32x16_bf16 v[112:127], v[156:159], v[148:151], v[112:127]
	v_mfma_f32_32x32x16_bf16 v[96:111], v[140:143], v[148:151], v[96:111]
	v_mfma_f32_32x32x16_bf16 v[80:95], v[136:139], v[148:151], v[80:95]
	v_mfma_f32_32x32x16_bf16 v[64:79], v[132:135], v[148:151], v[64:79]
	ds_read_b128 v[128:131], v169 offset:41536
	ds_read_b128 v[132:135], v169 offset:36928
	ds_read_b128 v[136:139], v168 offset:50752
	ds_read_b128 v[140:143], v168 offset:46144
	ds_read_b128 v[144:147], v168 offset:41536
	ds_read_b128 v[148:151], v168 offset:36928
	s_waitcnt lgkmcnt(0)
	v_mfma_f32_32x32x16_bf16 v[48:63], v[148:151], v[128:131], v[48:63]
	v_mfma_f32_32x32x16_bf16 v[32:47], v[144:147], v[128:131], v[32:47]
	v_mfma_f32_32x32x16_bf16 v[16:31], v[140:143], v[128:131], v[16:31]
	v_mfma_f32_32x32x16_bf16 v[0:15], v[136:139], v[128:131], v[0:15]
	v_mfma_f32_32x32x16_bf16 v[112:127], v[148:151], v[132:135], v[112:127]
	v_mfma_f32_32x32x16_bf16 v[96:111], v[144:147], v[132:135], v[96:111]
	v_mfma_f32_32x32x16_bf16 v[80:95], v[140:143], v[132:135], v[80:95]
	v_mfma_f32_32x32x16_bf16 v[64:79], v[136:139], v[132:135], v[64:79]
	ds_read_b128 v[128:131], v169 offset:41568
	ds_read_b128 v[132:135], v169 offset:36960
	ds_read_b128 v[136:139], v168 offset:50784
	ds_read_b128 v[140:143], v168 offset:46176
	ds_read_b128 v[144:147], v168 offset:41568
	ds_read_b128 v[148:151], v168 offset:36960
	s_waitcnt lgkmcnt(0)
	s_barrier
	v_mfma_f32_32x32x16_bf16 v[48:63], v[148:151], v[128:131], v[48:63]
	v_mfma_f32_32x32x16_bf16 v[32:47], v[144:147], v[128:131], v[32:47]
	v_mfma_f32_32x32x16_bf16 v[16:31], v[140:143], v[128:131], v[16:31]
	v_mfma_f32_32x32x16_bf16 v[0:15], v[136:139], v[128:131], v[0:15]
	v_mov_b32_e32 v130, v192
	s_nop 0
	v_ashrrev_i32_e32 v128, 1, v130
	v_and_b32_e32 v128, 0xffffff80, v128
	v_lshrrev_b32_e32 v129, 3, v130
	v_and_b32_e32 v131, 0xdf, v130
	v_mfma_f32_32x32x16_bf16 v[112:127], v[148:151], v[132:135], v[112:127]
	v_mul_u32_u24_e32 v131, 0x208, v131
	v_mfma_f32_32x32x16_bf16 v[96:111], v[144:147], v[132:135], v[96:111]
	v_mfma_f32_32x32x16_bf16 v[80:95], v[140:143], v[132:135], v[80:95]
	v_mfma_f32_32x32x16_bf16 v[64:79], v[136:139], v[132:135], v[64:79]
	v_and_b32_e32 v132, 4, v129
	v_ashrrev_i32_e32 v129, 31, v128
	v_or_b32_e32 v133, v128, v132
	v_lshl_add_u64 v[128:129], v[128:129], 2, s[12:13]
	v_lshlrev_b32_e32 v160, 2, v132
	v_lshl_add_u64 v[128:129], v[128:129], 0, v[160:161]
	v_lshl_add_u32 v131, v133, 1, v131
	global_load_dwordx4 v[196:199], v[128:129], off
	global_load_dwordx4 v[200:203], v[128:129], off offset:32
	global_load_dwordx4 v[204:207], v[128:129], off offset:64
	global_load_dwordx4 v[208:211], v[128:129], off offset:96
	global_load_dwordx4 v[212:215], v[128:129], off offset:128
	global_load_dwordx4 v[216:219], v[128:129], off offset:160
	global_load_dwordx4 v[220:223], v[128:129], off offset:192
	global_load_dwordx4 v[224:227], v[128:129], off offset:224
	global_load_dwordx4 v[228:231], v[128:129], off offset:256
	global_load_dwordx4 v[232:235], v[128:129], off offset:288
	global_load_dwordx4 v[236:239], v[128:129], off offset:320
	global_load_dwordx4 v[240:243], v[128:129], off offset:352
	global_load_dwordx4 v[248:251], v[128:129], off offset:384
	global_load_dwordx4 v[252:255], v[128:129], off offset:416
	s_waitcnt vmcnt(13)
	v_mov_b32_e32 v132, v196
	v_mov_b32_e32 v133, v197
	v_mov_b32_e32 v134, v198
	v_mov_b32_e32 v135, v199
	v_pk_add_f32 v[112:113], v[112:113], v[132:133]
	s_nop 0
	v_mul_f32_e32 v132, 0xbfb8aa3b, v112
	v_mul_f32_e32 v133, 0xbfb8aa3b, v113
	v_exp_f32_e32 v132, v132
	v_exp_f32_e32 v133, v133
	v_pk_add_f32 v[114:115], v[114:115], v[134:135]
	v_add_f32_e32 v132, 1.0, v132
	v_add_f32_e32 v133, 1.0, v133
	v_rcp_f32_e32 v132, v132
	v_rcp_f32_e32 v133, v133
	s_nop 0
	v_pk_mul_f32 v[112:113], v[112:113], v[132:133]
	v_mul_f32_e32 v132, 0xbfb8aa3b, v114
	v_mul_f32_e32 v133, 0xbfb8aa3b, v115
	v_exp_f32_e32 v132, v132
	v_exp_f32_e32 v133, v133
	v_add_f32_e32 v132, 1.0, v132
	v_add_f32_e32 v133, 1.0, v133
	v_rcp_f32_e32 v132, v132
	v_rcp_f32_e32 v133, v133
	s_nop 0
	v_pk_mul_f32 v[114:115], v[114:115], v[132:133]
	v_cvt_pk_bf16_f32 v132, v112, v113
	v_cvt_pk_bf16_f32 v133, v114, v115
	s_waitcnt vmcnt(12)
	v_mov_b32_e32 v112, v200
	v_mov_b32_e32 v113, v201
	v_mov_b32_e32 v114, v202
	v_mov_b32_e32 v115, v203
	v_pk_add_f32 v[112:113], v[116:117], v[112:113]
	s_nop 0
	v_mul_f32_e32 v116, 0xbfb8aa3b, v112
	v_mul_f32_e32 v117, 0xbfb8aa3b, v113
	v_exp_f32_e32 v116, v116
	v_exp_f32_e32 v117, v117
	v_pk_add_f32 v[114:115], v[118:119], v[114:115]
	v_add_f32_e32 v116, 1.0, v116
	v_add_f32_e32 v117, 1.0, v117
	v_rcp_f32_e32 v116, v116
	v_rcp_f32_e32 v117, v117
	s_nop 0
	v_pk_mul_f32 v[112:113], v[112:113], v[116:117]
	v_mul_f32_e32 v116, 0xbfb8aa3b, v114
	v_mul_f32_e32 v117, 0xbfb8aa3b, v115
	v_exp_f32_e32 v116, v116
	v_exp_f32_e32 v117, v117
	v_cvt_pk_bf16_f32 v112, v112, v113
	v_add_f32_e32 v116, 1.0, v116
	v_add_f32_e32 v117, 1.0, v117
	v_rcp_f32_e32 v116, v116
	v_rcp_f32_e32 v117, v117
	s_nop 0
	v_pk_mul_f32 v[114:115], v[114:115], v[116:117]
	s_nop 0
	v_cvt_pk_bf16_f32 v113, v114, v115
	ds_write2_b64 v131, v[132:133], v[112:113] offset1:2
	s_waitcnt vmcnt(11)
; DI unsigned pack2(float a, float b) { f32x2_t v = {a, b}; bf16x2_t r = __builtin_convertvector(v, bf16x2_t); return __builtin_bit_cast(unsigned, r); }
; DI float bflo(unsigned u) { return __uint_as_float(u << 16); }
; DI float bfhi(unsigned u) { return __uint_as_float(u & 0xffff0000u); }
; DI float siluf_(float x) { return x * __builtin_amdgcn_rcpf(1.f + __expf(-x)); }
; DI void epi_seg(const f32x16 (&acc)[4][2], const Seg& sg0, const Seg& sg1, int m0, int n0, const float* rs, const float2* cs64, const float2* cs32, bf16_t* stg) {
;     ...
;         for (int ch = 0; ch < 2; ++ch) {
;           float ss = 0.f;
; #pragma unroll
;           for (int i = 2 * ch; i < 2 * ch + 2; ++i)
; #pragma unroll
;             for (int q4 = 0; q4 < 4; ++q4) {
;               float v[4] = {acc[i][j][4 * q4] * sc, acc[i][j][4 * q4 + 1] * sc, acc[i][j][4 * q4 + 2] * sc, acc[i][j][4 * q4 + 3] * sc};
;               if (kind == K_SILU) {
;                 const f32x4 bv = *(const f32x4*)(sg.bias + lcw + i * 32 + 8 * q4 + 4 * h);
;                 v[0] = siluf_(v[0] + bv.x); v[1] = siluf_(v[1] + bv.y); v[2] = siluf_(v[2] + bv.z); v[3] = siluf_(v[3] + bv.w);
;               }
;               const uint2 pk = make_uint2(pack2(v[0], v[1]), pack2(v[2], v[3]));
;               *(uint2*)(srow + i * 32 + 8 * q4) = pk;
;               const float f0 = bflo(pk.x), f1 = bfhi(pk.x), f2 = bflo(pk.y), f3 = bfhi(pk.y);
;               ss += (f0 * f0 + f1 * f1) + (f2 * f2 + f3 * f3);
;             }
	v_mov_b32_e32 v112, v204
	v_mov_b32_e32 v113, v205
	v_mov_b32_e32 v114, v206
	v_mov_b32_e32 v115, v207
	v_pk_add_f32 v[112:113], v[120:121], v[112:113]
	s_nop 0
	v_mul_f32_e32 v116, 0xbfb8aa3b, v112
	v_mul_f32_e32 v117, 0xbfb8aa3b, v113
	v_exp_f32_e32 v116, v116
	v_exp_f32_e32 v117, v117
	v_pk_add_f32 v[114:115], v[122:123], v[114:115]
	v_add_f32_e32 v116, 1.0, v116
	v_add_f32_e32 v117, 1.0, v117
	v_rcp_f32_e32 v116, v116
	v_rcp_f32_e32 v117, v117
	s_nop 0
	v_pk_mul_f32 v[112:113], v[112:113], v[116:117]
	v_mul_f32_e32 v116, 0xbfb8aa3b, v114
	v_mul_f32_e32 v117, 0xbfb8aa3b, v115
	v_exp_f32_e32 v116, v116
	v_exp_f32_e32 v117, v117
	v_add_f32_e32 v116, 1.0, v116
	v_add_f32_e32 v117, 1.0, v117
	v_rcp_f32_e32 v116, v116
	v_rcp_f32_e32 v117, v117
	s_nop 0
	v_pk_mul_f32 v[114:115], v[114:115], v[116:117]
	v_cvt_pk_bf16_f32 v116, v112, v113
	v_cvt_pk_bf16_f32 v117, v114, v115
	s_waitcnt vmcnt(10)
	v_mov_b32_e32 v112, v208
	v_mov_b32_e32 v113, v209
	v_mov_b32_e32 v114, v210
	v_mov_b32_e32 v115, v211
	v_pk_add_f32 v[112:113], v[124:125], v[112:113]
	s_nop 0
	v_mul_f32_e32 v118, 0xbfb8aa3b, v112
	v_mul_f32_e32 v119, 0xbfb8aa3b, v113
	v_exp_f32_e32 v118, v118
	v_exp_f32_e32 v119, v119
	v_pk_add_f32 v[114:115], v[126:127], v[114:115]
	v_add_f32_e32 v118, 1.0, v118
	v_add_f32_e32 v119, 1.0, v119
	v_rcp_f32_e32 v118, v118
	v_rcp_f32_e32 v119, v119
	s_nop 0
	v_pk_mul_f32 v[112:113], v[112:113], v[118:119]
	v_mul_f32_e32 v118, 0xbfb8aa3b, v114
	v_mul_f32_e32 v119, 0xbfb8aa3b, v115
	v_exp_f32_e32 v118, v118
	v_exp_f32_e32 v119, v119
	v_cvt_pk_bf16_f32 v112, v112, v113
	v_add_f32_e32 v118, 1.0, v118
	v_add_f32_e32 v119, 1.0, v119
	v_rcp_f32_e32 v118, v118
	v_rcp_f32_e32 v119, v119
	s_nop 0
	v_pk_mul_f32 v[114:115], v[114:115], v[118:119]
	s_nop 0
	v_cvt_pk_bf16_f32 v113, v114, v115
	ds_write2_b64 v131, v[116:117], v[112:113] offset0:4 offset1:6
	s_waitcnt vmcnt(9)
	v_mov_b32_e32 v112, v212
	v_mov_b32_e32 v113, v213
	v_mov_b32_e32 v114, v214
	v_mov_b32_e32 v115, v215
	v_pk_add_f32 v[96:97], v[96:97], v[112:113]
	s_nop 0
	v_mul_f32_e32 v112, 0xbfb8aa3b, v96
	v_mul_f32_e32 v113, 0xbfb8aa3b, v97
	v_exp_f32_e32 v112, v112
	v_exp_f32_e32 v113, v113
	v_pk_add_f32 v[98:99], v[98:99], v[114:115]
	v_add_f32_e32 v112, 1.0, v112
	v_add_f32_e32 v113, 1.0, v113
	v_rcp_f32_e32 v112, v112
	v_rcp_f32_e32 v113, v113
	s_nop 0
	v_pk_mul_f32 v[96:97], v[96:97], v[112:113]
	v_mul_f32_e32 v112, 0xbfb8aa3b, v98
	v_mul_f32_e32 v113, 0xbfb8aa3b, v99
	v_exp_f32_e32 v112, v112
	v_exp_f32_e32 v113, v113
	v_add_f32_e32 v112, 1.0, v112
	v_add_f32_e32 v113, 1.0, v113
	v_rcp_f32_e32 v112, v112
	v_rcp_f32_e32 v113, v113
	s_nop 0
	v_pk_mul_f32 v[98:99], v[98:99], v[112:113]
	v_cvt_pk_bf16_f32 v112, v96, v97
	v_cvt_pk_bf16_f32 v113, v98, v99
	s_waitcnt vmcnt(8)
	v_mov_b32_e32 v96, v216
	v_mov_b32_e32 v97, v217
	v_mov_b32_e32 v98, v218
	v_mov_b32_e32 v99, v219
	v_pk_add_f32 v[96:97], v[100:101], v[96:97]
	s_nop 0
	v_mul_f32_e32 v100, 0xbfb8aa3b, v96
	v_mul_f32_e32 v101, 0xbfb8aa3b, v97
	v_exp_f32_e32 v100, v100
	v_exp_f32_e32 v101, v101
	v_pk_add_f32 v[98:99], v[102:103], v[98:99]
	v_add_f32_e32 v100, 1.0, v100
	v_add_f32_e32 v101, 1.0, v101
	v_rcp_f32_e32 v100, v100
	v_rcp_f32_e32 v101, v101
	s_nop 0
	v_pk_mul_f32 v[96:97], v[96:97], v[100:101]
	v_mul_f32_e32 v100, 0xbfb8aa3b, v98
	v_mul_f32_e32 v101, 0xbfb8aa3b, v99
	v_exp_f32_e32 v100, v100
	v_exp_f32_e32 v101, v101
	v_cvt_pk_bf16_f32 v96, v96, v97
	v_add_f32_e32 v100, 1.0, v100
	v_add_f32_e32 v101, 1.0, v101
	v_rcp_f32_e32 v100, v100
	v_rcp_f32_e32 v101, v101
	s_nop 0
	v_pk_mul_f32 v[98:99], v[98:99], v[100:101]
	s_nop 0
	v_cvt_pk_bf16_f32 v97, v98, v99
	ds_write2_b64 v131, v[112:113], v[96:97] offset0:8 offset1:10
	s_waitcnt vmcnt(7)
	v_mov_b32_e32 v96, v220
	v_mov_b32_e32 v97, v221
	v_mov_b32_e32 v98, v222
	v_mov_b32_e32 v99, v223
	v_pk_add_f32 v[96:97], v[104:105], v[96:97]
	s_nop 0
	v_mul_f32_e32 v100, 0xbfb8aa3b, v96
	v_mul_f32_e32 v101, 0xbfb8aa3b, v97
	v_exp_f32_e32 v100, v100
	v_exp_f32_e32 v101, v101
	v_pk_add_f32 v[98:99], v[106:107], v[98:99]
	v_add_f32_e32 v100, 1.0, v100
	v_add_f32_e32 v101, 1.0, v101
	v_rcp_f32_e32 v100, v100
	v_rcp_f32_e32 v101, v101
	s_nop 0
	v_pk_mul_f32 v[96:97], v[96:97], v[100:101]
	v_mul_f32_e32 v100, 0xbfb8aa3b, v98
	v_mul_f32_e32 v101, 0xbfb8aa3b, v99
	v_exp_f32_e32 v100, v100
	v_exp_f32_e32 v101, v101
	v_add_f32_e32 v100, 1.0, v100
	v_add_f32_e32 v101, 1.0, v101
	v_rcp_f32_e32 v100, v100
	v_rcp_f32_e32 v101, v101
	s_nop 0
	v_pk_mul_f32 v[98:99], v[98:99], v[100:101]
	v_cvt_pk_bf16_f32 v100, v96, v97
	v_cvt_pk_bf16_f32 v101, v98, v99
	s_waitcnt vmcnt(6)
	v_mov_b32_e32 v96, v224
	v_mov_b32_e32 v97, v225
	v_mov_b32_e32 v98, v226
	v_mov_b32_e32 v99, v227
	v_pk_add_f32 v[96:97], v[108:109], v[96:97]
	s_nop 0
	v_mul_f32_e32 v102, 0xbfb8aa3b, v96
	v_mul_f32_e32 v103, 0xbfb8aa3b, v97
	v_exp_f32_e32 v102, v102
	v_exp_f32_e32 v103, v103
	v_pk_add_f32 v[98:99], v[110:111], v[98:99]
	v_add_f32_e32 v102, 1.0, v102
	v_add_f32_e32 v103, 1.0, v103
	v_rcp_f32_e32 v102, v102
	v_rcp_f32_e32 v103, v103
	s_nop 0
	v_pk_mul_f32 v[96:97], v[96:97], v[102:103]
	v_mul_f32_e32 v102, 0xbfb8aa3b, v98
	v_mul_f32_e32 v103, 0xbfb8aa3b, v99
	v_exp_f32_e32 v102, v102
	v_exp_f32_e32 v103, v103
	v_cvt_pk_bf16_f32 v96, v96, v97
	v_add_f32_e32 v102, 1.0, v102
	v_add_f32_e32 v103, 1.0, v103
	v_rcp_f32_e32 v102, v102
	v_rcp_f32_e32 v103, v103
	s_nop 0
	v_pk_mul_f32 v[98:99], v[98:99], v[102:103]
	s_nop 0
	v_cvt_pk_bf16_f32 v97, v98, v99
	ds_write2_b64 v131, v[100:101], v[96:97] offset0:12 offset1:14
	s_waitcnt vmcnt(5)
; DI unsigned pack2(float a, float b) { f32x2_t v = {a, b}; bf16x2_t r = __builtin_convertvector(v, bf16x2_t); return __builtin_bit_cast(unsigned, r); }
; DI float bflo(unsigned u) { return __uint_as_float(u << 16); }
; DI float bfhi(unsigned u) { return __uint_as_float(u & 0xffff0000u); }
; DI float siluf_(float x) { return x * __builtin_amdgcn_rcpf(1.f + __expf(-x)); }
; DI void epi_seg(const f32x16 (&acc)[4][2], const Seg& sg0, const Seg& sg1, int m0, int n0, const float* rs, const float2* cs64, const float2* cs32, bf16_t* stg) {
;     ...
;         for (int ch = 0; ch < 2; ++ch) {
;           float ss = 0.f;
; #pragma unroll
;           for (int i = 2 * ch; i < 2 * ch + 2; ++i)
; #pragma unroll
;             for (int q4 = 0; q4 < 4; ++q4) {
;               float v[4] = {acc[i][j][4 * q4] * sc, acc[i][j][4 * q4 + 1] * sc, acc[i][j][4 * q4 + 2] * sc, acc[i][j][4 * q4 + 3] * sc};
;               if (kind == K_SILU) {
;                 const f32x4 bv = *(const f32x4*)(sg.bias + lcw + i * 32 + 8 * q4 + 4 * h);
;                 v[0] = siluf_(v[0] + bv.x); v[1] = siluf_(v[1] + bv.y); v[2] = siluf_(v[2] + bv.z); v[3] = siluf_(v[3] + bv.w);
;               }
;               const uint2 pk = make_uint2(pack2(v[0], v[1]), pack2(v[2], v[3]));
;               *(uint2*)(srow + i * 32 + 8 * q4) = pk;
;               const float f0 = bflo(pk.x), f1 = bfhi(pk.x), f2 = bflo(pk.y), f3 = bfhi(pk.y);
;               ss += (f0 * f0 + f1 * f1) + (f2 * f2 + f3 * f3);
;             }
	v_mov_b32_e32 v96, v228
	v_mov_b32_e32 v97, v229
	v_mov_b32_e32 v98, v230
	v_mov_b32_e32 v99, v231
	v_pk_add_f32 v[80:81], v[80:81], v[96:97]
	s_nop 0
	v_mul_f32_e32 v96, 0xbfb8aa3b, v80
	v_mul_f32_e32 v97, 0xbfb8aa3b, v81
	v_exp_f32_e32 v96, v96
	v_exp_f32_e32 v97, v97
	v_pk_add_f32 v[82:83], v[82:83], v[98:99]
	v_add_f32_e32 v96, 1.0, v96
	v_add_f32_e32 v97, 1.0, v97
	v_rcp_f32_e32 v96, v96
	v_rcp_f32_e32 v97, v97
	s_nop 0
	v_pk_mul_f32 v[80:81], v[80:81], v[96:97]
	v_mul_f32_e32 v96, 0xbfb8aa3b, v82
	v_mul_f32_e32 v97, 0xbfb8aa3b, v83
	v_exp_f32_e32 v96, v96
	v_exp_f32_e32 v97, v97
	v_add_f32_e32 v96, 1.0, v96
	v_add_f32_e32 v97, 1.0, v97
	v_rcp_f32_e32 v96, v96
	v_rcp_f32_e32 v97, v97
	s_nop 0
	v_pk_mul_f32 v[82:83], v[82:83], v[96:97]
	v_cvt_pk_bf16_f32 v96, v80, v81
	v_cvt_pk_bf16_f32 v97, v82, v83
	s_waitcnt vmcnt(4)
	v_mov_b32_e32 v80, v232
	v_mov_b32_e32 v81, v233
	v_mov_b32_e32 v82, v234
	v_mov_b32_e32 v83, v235
	v_pk_add_f32 v[80:81], v[84:85], v[80:81]
	s_nop 0
	v_mul_f32_e32 v84, 0xbfb8aa3b, v80
	v_mul_f32_e32 v85, 0xbfb8aa3b, v81
	v_exp_f32_e32 v84, v84
	v_exp_f32_e32 v85, v85
	v_pk_add_f32 v[82:83], v[86:87], v[82:83]
	v_add_f32_e32 v84, 1.0, v84
	v_add_f32_e32 v85, 1.0, v85
	v_rcp_f32_e32 v84, v84
	v_rcp_f32_e32 v85, v85
	s_nop 0
	v_pk_mul_f32 v[80:81], v[80:81], v[84:85]
	v_mul_f32_e32 v84, 0xbfb8aa3b, v82
	v_mul_f32_e32 v85, 0xbfb8aa3b, v83
	v_exp_f32_e32 v84, v84
	v_exp_f32_e32 v85, v85
	v_cvt_pk_bf16_f32 v80, v80, v81
	v_add_f32_e32 v84, 1.0, v84
	v_add_f32_e32 v85, 1.0, v85
	v_rcp_f32_e32 v84, v84
	v_rcp_f32_e32 v85, v85
	s_nop 0
	v_pk_mul_f32 v[82:83], v[82:83], v[84:85]
	s_nop 0
	v_cvt_pk_bf16_f32 v81, v82, v83
	ds_write2_b64 v131, v[96:97], v[80:81] offset0:16 offset1:18
	s_waitcnt vmcnt(3)
	v_mov_b32_e32 v80, v236
	v_mov_b32_e32 v81, v237
	v_mov_b32_e32 v82, v238
	v_mov_b32_e32 v83, v239
	v_pk_add_f32 v[80:81], v[88:89], v[80:81]
	s_nop 0
	v_mul_f32_e32 v84, 0xbfb8aa3b, v80
	v_mul_f32_e32 v85, 0xbfb8aa3b, v81
	v_exp_f32_e32 v84, v84
	v_exp_f32_e32 v85, v85
	v_pk_add_f32 v[82:83], v[90:91], v[82:83]
	v_add_f32_e32 v84, 1.0, v84
	v_add_f32_e32 v85, 1.0, v85
	v_rcp_f32_e32 v84, v84
	v_rcp_f32_e32 v85, v85
	s_nop 0
	v_pk_mul_f32 v[80:81], v[80:81], v[84:85]
	v_mul_f32_e32 v84, 0xbfb8aa3b, v82
	v_mul_f32_e32 v85, 0xbfb8aa3b, v83
	v_exp_f32_e32 v84, v84
	v_exp_f32_e32 v85, v85
	v_add_f32_e32 v84, 1.0, v84
	v_add_f32_e32 v85, 1.0, v85
	v_rcp_f32_e32 v84, v84
	v_rcp_f32_e32 v85, v85
	s_nop 0
	v_pk_mul_f32 v[82:83], v[82:83], v[84:85]
	v_cvt_pk_bf16_f32 v84, v80, v81
	v_cvt_pk_bf16_f32 v85, v82, v83
	s_waitcnt vmcnt(2)
	v_mov_b32_e32 v80, v240
	v_mov_b32_e32 v81, v241
	v_mov_b32_e32 v82, v242
	v_mov_b32_e32 v83, v243
	v_pk_add_f32 v[80:81], v[92:93], v[80:81]
	s_nop 0
	v_mul_f32_e32 v86, 0xbfb8aa3b, v80
	v_mul_f32_e32 v87, 0xbfb8aa3b, v81
	v_exp_f32_e32 v86, v86
	v_exp_f32_e32 v87, v87
	v_pk_add_f32 v[82:83], v[94:95], v[82:83]
	v_add_f32_e32 v86, 1.0, v86
	v_add_f32_e32 v87, 1.0, v87
	v_rcp_f32_e32 v86, v86
	v_rcp_f32_e32 v87, v87
	s_nop 0
	v_pk_mul_f32 v[80:81], v[80:81], v[86:87]
	v_mul_f32_e32 v86, 0xbfb8aa3b, v82
	v_mul_f32_e32 v87, 0xbfb8aa3b, v83
	v_exp_f32_e32 v86, v86
	v_exp_f32_e32 v87, v87
	v_cvt_pk_bf16_f32 v80, v80, v81
	v_add_f32_e32 v86, 1.0, v86
	v_add_f32_e32 v87, 1.0, v87
	v_rcp_f32_e32 v86, v86
	v_rcp_f32_e32 v87, v87
	s_nop 0
	v_pk_mul_f32 v[82:83], v[82:83], v[86:87]
	s_nop 0
	v_cvt_pk_bf16_f32 v81, v82, v83
	ds_write2_b64 v131, v[84:85], v[80:81] offset0:20 offset1:22
	s_waitcnt vmcnt(1)
	v_mov_b32_e32 v80, v248
	v_mov_b32_e32 v81, v249
	v_mov_b32_e32 v82, v250
	v_mov_b32_e32 v83, v251
	v_pk_add_f32 v[64:65], v[64:65], v[80:81]
	s_nop 0
	v_mul_f32_e32 v80, 0xbfb8aa3b, v64
	v_mul_f32_e32 v81, 0xbfb8aa3b, v65
	v_exp_f32_e32 v80, v80
	v_exp_f32_e32 v81, v81
	v_pk_add_f32 v[66:67], v[66:67], v[82:83]
	v_add_f32_e32 v80, 1.0, v80
	v_add_f32_e32 v81, 1.0, v81
	v_rcp_f32_e32 v80, v80
	v_rcp_f32_e32 v81, v81
	s_nop 0
	v_pk_mul_f32 v[64:65], v[64:65], v[80:81]
	v_mul_f32_e32 v80, 0xbfb8aa3b, v66
	v_mul_f32_e32 v81, 0xbfb8aa3b, v67
	v_exp_f32_e32 v80, v80
	v_exp_f32_e32 v81, v81
	v_add_f32_e32 v80, 1.0, v80
	v_add_f32_e32 v81, 1.0, v81
	v_rcp_f32_e32 v80, v80
	v_rcp_f32_e32 v81, v81
	s_nop 0
	v_pk_mul_f32 v[66:67], v[66:67], v[80:81]
	v_cvt_pk_bf16_f32 v80, v64, v65
	v_cvt_pk_bf16_f32 v81, v66, v67
	s_waitcnt vmcnt(0)
	v_mov_b32_e32 v64, v252
	v_mov_b32_e32 v65, v253
	v_mov_b32_e32 v66, v254
	v_mov_b32_e32 v67, v255
	v_pk_add_f32 v[64:65], v[68:69], v[64:65]
	s_nop 0
	v_mul_f32_e32 v68, 0xbfb8aa3b, v64
	v_mul_f32_e32 v69, 0xbfb8aa3b, v65
	v_exp_f32_e32 v68, v68
	v_exp_f32_e32 v69, v69
	v_pk_add_f32 v[66:67], v[70:71], v[66:67]
	v_add_f32_e32 v68, 1.0, v68
	v_add_f32_e32 v69, 1.0, v69
	v_rcp_f32_e32 v68, v68
	v_rcp_f32_e32 v69, v69
	s_nop 0
	v_pk_mul_f32 v[64:65], v[64:65], v[68:69]
	v_mul_f32_e32 v68, 0xbfb8aa3b, v66
	v_mul_f32_e32 v69, 0xbfb8aa3b, v67
	v_exp_f32_e32 v68, v68
	v_exp_f32_e32 v69, v69
	v_cvt_pk_bf16_f32 v64, v64, v65
	v_add_f32_e32 v68, 1.0, v68
	v_add_f32_e32 v69, 1.0, v69
	v_rcp_f32_e32 v68, v68
	v_rcp_f32_e32 v69, v69
	s_nop 0
	v_pk_mul_f32 v[66:67], v[66:67], v[68:69]
	s_nop 0
	v_cvt_pk_bf16_f32 v65, v66, v67
	ds_write2_b64 v131, v[80:81], v[64:65] offset0:24 offset1:26
	global_load_dwordx4 v[64:67], v[128:129], off offset:448
	s_waitcnt vmcnt(0)
; DI unsigned pack2(float a, float b) { f32x2_t v = {a, b}; bf16x2_t r = __builtin_convertvector(v, bf16x2_t); return __builtin_bit_cast(unsigned, r); }
; DI float bflo(unsigned u) { return __uint_as_float(u << 16); }
; DI float bfhi(unsigned u) { return __uint_as_float(u & 0xffff0000u); }
; DI float siluf_(float x) { return x * __builtin_amdgcn_rcpf(1.f + __expf(-x)); }
; DI void epi_seg(const f32x16 (&acc)[4][2], const Seg& sg0, const Seg& sg1, int m0, int n0, const float* rs, const float2* cs64, const float2* cs32, bf16_t* stg) {
;     ...
;         for (int ch = 0; ch < 2; ++ch) {
;           float ss = 0.f;
; #pragma unroll
;           for (int i = 2 * ch; i < 2 * ch + 2; ++i)
; #pragma unroll
;             for (int q4 = 0; q4 < 4; ++q4) {
;               float v[4] = {acc[i][j][4 * q4] * sc, acc[i][j][4 * q4 + 1] * sc, acc[i][j][4 * q4 + 2] * sc, acc[i][j][4 * q4 + 3] * sc};
;               if (kind == K_SILU) {
;                 const f32x4 bv = *(const f32x4*)(sg.bias + lcw + i * 32 + 8 * q4 + 4 * h);
;                 v[0] = siluf_(v[0] + bv.x); v[1] = siluf_(v[1] + bv.y); v[2] = siluf_(v[2] + bv.z); v[3] = siluf_(v[3] + bv.w);
;               }
;               const uint2 pk = make_uint2(pack2(v[0], v[1]), pack2(v[2], v[3]));
;               *(uint2*)(srow + i * 32 + 8 * q4) = pk;
;               const float f0 = bflo(pk.x), f1 = bfhi(pk.x), f2 = bflo(pk.y), f3 = bfhi(pk.y);
;               ss += (f0 * f0 + f1 * f1) + (f2 * f2 + f3 * f3);
;             }
	v_pk_add_f32 v[64:65], v[72:73], v[64:65]
	s_nop 0
	v_mul_f32_e32 v68, 0xbfb8aa3b, v64
	v_mul_f32_e32 v69, 0xbfb8aa3b, v65
	v_exp_f32_e32 v68, v68
	v_exp_f32_e32 v69, v69
	v_pk_add_f32 v[66:67], v[74:75], v[66:67]
	v_add_f32_e32 v68, 1.0, v68
	v_add_f32_e32 v69, 1.0, v69
	v_rcp_f32_e32 v68, v68
	v_rcp_f32_e32 v69, v69
	s_nop 0
	v_pk_mul_f32 v[64:65], v[64:65], v[68:69]
	v_mul_f32_e32 v68, 0xbfb8aa3b, v66
	v_mul_f32_e32 v69, 0xbfb8aa3b, v67
	v_exp_f32_e32 v68, v68
	v_exp_f32_e32 v69, v69
	v_add_f32_e32 v68, 1.0, v68
	v_add_f32_e32 v69, 1.0, v69
	v_rcp_f32_e32 v68, v68
	v_rcp_f32_e32 v69, v69
	s_nop 0
	v_pk_mul_f32 v[66:67], v[66:67], v[68:69]
	v_cvt_pk_bf16_f32 v68, v64, v65
	v_cvt_pk_bf16_f32 v69, v66, v67
	global_load_dwordx4 v[64:67], v[128:129], off offset:480
	s_waitcnt vmcnt(0)
	v_pk_add_f32 v[64:65], v[76:77], v[64:65]
	s_nop 0
	v_mul_f32_e32 v70, 0xbfb8aa3b, v64
	v_mul_f32_e32 v71, 0xbfb8aa3b, v65
	v_exp_f32_e32 v70, v70
	v_exp_f32_e32 v71, v71
	v_pk_add_f32 v[66:67], v[78:79], v[66:67]
	v_add_f32_e32 v70, 1.0, v70
	v_add_f32_e32 v71, 1.0, v71
	v_rcp_f32_e32 v70, v70
	v_rcp_f32_e32 v71, v71
	s_nop 0
	v_pk_mul_f32 v[64:65], v[64:65], v[70:71]
	v_mul_f32_e32 v70, 0xbfb8aa3b, v66
	v_mul_f32_e32 v71, 0xbfb8aa3b, v67
	v_exp_f32_e32 v70, v70
	v_exp_f32_e32 v71, v71
	v_cvt_pk_bf16_f32 v64, v64, v65
	v_add_f32_e32 v70, 1.0, v70
	v_add_f32_e32 v71, 1.0, v71
	v_rcp_f32_e32 v70, v70
	v_rcp_f32_e32 v71, v71
	s_nop 0
	v_pk_mul_f32 v[66:67], v[66:67], v[70:71]
	s_nop 0
	v_cvt_pk_bf16_f32 v65, v66, v67
	ds_write2_b64 v131, v[68:69], v[64:65] offset0:28 offset1:30
	v_mov_b32_e32 v64, v196
	v_mov_b32_e32 v65, v197
	v_mov_b32_e32 v66, v198
	v_mov_b32_e32 v67, v199
	v_pk_add_f32 v[48:49], v[48:49], v[64:65]
	s_nop 0
	v_mul_f32_e32 v64, 0xbfb8aa3b, v48
	v_mul_f32_e32 v65, 0xbfb8aa3b, v49
	v_exp_f32_e32 v64, v64
	v_exp_f32_e32 v65, v65
	v_pk_add_f32 v[50:51], v[50:51], v[66:67]
	v_add_f32_e32 v64, 1.0, v64
	v_add_f32_e32 v65, 1.0, v65
	v_rcp_f32_e32 v64, v64
	v_rcp_f32_e32 v65, v65
	s_nop 0
	v_pk_mul_f32 v[48:49], v[48:49], v[64:65]
	v_mul_f32_e32 v64, 0xbfb8aa3b, v50
	v_mul_f32_e32 v65, 0xbfb8aa3b, v51
	v_exp_f32_e32 v64, v64
	v_exp_f32_e32 v65, v65
	v_add_f32_e32 v64, 1.0, v64
	v_add_f32_e32 v65, 1.0, v65
	v_rcp_f32_e32 v64, v64
	v_rcp_f32_e32 v65, v65
	s_nop 0
	v_pk_mul_f32 v[50:51], v[50:51], v[64:65]
	v_cvt_pk_bf16_f32 v64, v48, v49
	v_cvt_pk_bf16_f32 v65, v50, v51
	v_mov_b32_e32 v48, v200
	v_mov_b32_e32 v49, v201
	v_mov_b32_e32 v50, v202
	v_mov_b32_e32 v51, v203
	v_pk_add_f32 v[48:49], v[52:53], v[48:49]
	s_nop 0
	v_mul_f32_e32 v52, 0xbfb8aa3b, v48
	v_mul_f32_e32 v53, 0xbfb8aa3b, v49
	v_exp_f32_e32 v52, v52
	v_exp_f32_e32 v53, v53
	v_pk_add_f32 v[50:51], v[54:55], v[50:51]
	v_add_f32_e32 v52, 1.0, v52
	v_add_f32_e32 v53, 1.0, v53
	v_rcp_f32_e32 v52, v52
	v_rcp_f32_e32 v53, v53
	s_nop 0
	v_pk_mul_f32 v[48:49], v[48:49], v[52:53]
	v_mul_f32_e32 v52, 0xbfb8aa3b, v50
	v_mul_f32_e32 v53, 0xbfb8aa3b, v51
	v_exp_f32_e32 v52, v52
	v_exp_f32_e32 v53, v53
	v_add_f32_e32 v52, 1.0, v52
	v_add_f32_e32 v53, 1.0, v53
	v_rcp_f32_e32 v52, v52
	v_rcp_f32_e32 v53, v53
	s_nop 0
	v_pk_mul_f32 v[50:51], v[50:51], v[52:53]
	v_cvt_pk_bf16_f32 v52, v48, v49
	v_cvt_pk_bf16_f32 v53, v50, v51
	v_add_u32_e32 v48, 0x4000, v131
	ds_write2_b64 v48, v[64:65], v[52:53] offset0:32 offset1:34
	v_mov_b32_e32 v50, v204
	v_mov_b32_e32 v51, v205
	v_mov_b32_e32 v52, v206
	v_mov_b32_e32 v53, v207
	v_pk_add_f32 v[50:51], v[56:57], v[50:51]
	s_nop 0
	v_mul_f32_e32 v49, 0xbfb8aa3b, v50
	v_exp_f32_e32 v49, v49
	v_pk_add_f32 v[52:53], v[58:59], v[52:53]
	v_add_f32_e32 v49, 1.0, v49
	v_rcp_f32_e32 v54, v49
	v_mul_f32_e32 v49, 0xbfb8aa3b, v51
	v_exp_f32_e32 v49, v49
	s_nop 0
	v_add_f32_e32 v49, 1.0, v49
	v_rcp_f32_e32 v55, v49
	v_mul_f32_e32 v49, 0xbfb8aa3b, v52
	v_exp_f32_e32 v49, v49
	v_pk_mul_f32 v[50:51], v[50:51], v[54:55]
	v_add_f32_e32 v49, 1.0, v49
	v_rcp_f32_e32 v54, v49
	v_mul_f32_e32 v49, 0xbfb8aa3b, v53
	v_exp_f32_e32 v49, v49
	s_nop 0
	v_add_f32_e32 v49, 1.0, v49
	v_rcp_f32_e32 v55, v49
	s_nop 0
	v_pk_mul_f32 v[52:53], v[52:53], v[54:55]
	v_cvt_pk_bf16_f32 v54, v50, v51
	v_cvt_pk_bf16_f32 v55, v52, v53
	v_mov_b32_e32 v50, v208
	v_mov_b32_e32 v51, v209
	v_mov_b32_e32 v52, v210
	v_mov_b32_e32 v53, v211
	v_pk_add_f32 v[50:51], v[60:61], v[50:51]
	s_nop 0
	v_mul_f32_e32 v49, 0xbfb8aa3b, v50
	v_exp_f32_e32 v49, v49
	v_pk_add_f32 v[52:53], v[62:63], v[52:53]
	v_add_f32_e32 v49, 1.0, v49
	v_rcp_f32_e32 v56, v49
	v_mul_f32_e32 v49, 0xbfb8aa3b, v51
	v_exp_f32_e32 v49, v49
	s_nop 0
	v_add_f32_e32 v49, 1.0, v49
	v_rcp_f32_e32 v57, v49
	v_mul_f32_e32 v49, 0xbfb8aa3b, v52
	v_exp_f32_e32 v49, v49
	v_pk_mul_f32 v[50:51], v[50:51], v[56:57]
	s_nop 0
	v_cvt_pk_bf16_f32 v50, v50, v51
	v_add_f32_e32 v49, 1.0, v49
	v_rcp_f32_e32 v56, v49
	v_mul_f32_e32 v49, 0xbfb8aa3b, v53
	v_exp_f32_e32 v49, v49
	s_nop 0
	v_add_f32_e32 v49, 1.0, v49
	v_rcp_f32_e32 v57, v49
	s_nop 0
	v_pk_mul_f32 v[52:53], v[52:53], v[56:57]
	s_nop 0
	v_cvt_pk_bf16_f32 v51, v52, v53
	ds_write2_b64 v48, v[54:55], v[50:51] offset0:36 offset1:38
	v_mov_b32_e32 v50, v212
	v_mov_b32_e32 v51, v213
	v_mov_b32_e32 v52, v214
	v_mov_b32_e32 v53, v215
	v_pk_add_f32 v[32:33], v[32:33], v[50:51]
	s_nop 0
	v_mul_f32_e32 v49, 0xbfb8aa3b, v32
	v_exp_f32_e32 v49, v49
	v_pk_add_f32 v[34:35], v[34:35], v[52:53]
	v_add_f32_e32 v49, 1.0, v49
	v_rcp_f32_e32 v50, v49
	v_mul_f32_e32 v49, 0xbfb8aa3b, v33
	v_exp_f32_e32 v49, v49
	s_nop 0
	v_add_f32_e32 v49, 1.0, v49
	v_rcp_f32_e32 v51, v49
	v_mul_f32_e32 v49, 0xbfb8aa3b, v34
	v_exp_f32_e32 v49, v49
	v_pk_mul_f32 v[32:33], v[32:33], v[50:51]
	v_add_f32_e32 v49, 1.0, v49
	v_rcp_f32_e32 v50, v49
; DI unsigned pack2(float a, float b) { f32x2_t v = {a, b}; bf16x2_t r = __builtin_convertvector(v, bf16x2_t); return __builtin_bit_cast(unsigned, r); }
; DI float bflo(unsigned u) { return __uint_as_float(u << 16); }
; DI float bfhi(unsigned u) { return __uint_as_float(u & 0xffff0000u); }
; DI float siluf_(float x) { return x * __builtin_amdgcn_rcpf(1.f + __expf(-x)); }
; DI void epi_seg(const f32x16 (&acc)[4][2], const Seg& sg0, const Seg& sg1, int m0, int n0, const float* rs, const float2* cs64, const float2* cs32, bf16_t* stg) {
;     ...
; #pragma unroll
;         for (int ch = 0; ch < 2; ++ch) {
;           float ss = 0.f;
; #pragma unroll
;           for (int i = 2 * ch; i < 2 * ch + 2; ++i)
; #pragma unroll
;             for (int q4 = 0; q4 < 4; ++q4) {
;               float v[4] = {acc[i][j][4 * q4] * sc, acc[i][j][4 * q4 + 1] * sc, acc[i][j][4 * q4 + 2] * sc, acc[i][j][4 * q4 + 3] * sc};
;               if (kind == K_SILU) {
;                 const f32x4 bv = *(const f32x4*)(sg.bias + lcw + i * 32 + 8 * q4 + 4 * h);
;                 v[0] = siluf_(v[0] + bv.x); v[1] = siluf_(v[1] + bv.y); v[2] = siluf_(v[2] + bv.z); v[3] = siluf_(v[3] + bv.w);
;               }
;               const uint2 pk = make_uint2(pack2(v[0], v[1]), pack2(v[2], v[3]));
;               *(uint2*)(srow + i * 32 + 8 * q4) = pk;
;               const float f0 = bflo(pk.x), f1 = bfhi(pk.x), f2 = bflo(pk.y), f3 = bfhi(pk.y);
;               ss += (f0 * f0 + f1 * f1) + (f2 * f2 + f3 * f3);
;             }
	v_mul_f32_e32 v49, 0xbfb8aa3b, v35
	v_exp_f32_e32 v49, v49
	s_nop 0
	v_add_f32_e32 v49, 1.0, v49
	v_rcp_f32_e32 v51, v49
	s_nop 0
	v_pk_mul_f32 v[34:35], v[34:35], v[50:51]
	v_cvt_pk_bf16_f32 v50, v32, v33
	v_cvt_pk_bf16_f32 v51, v34, v35
	v_mov_b32_e32 v32, v216
	v_mov_b32_e32 v33, v217
	v_mov_b32_e32 v34, v218
	v_mov_b32_e32 v35, v219
	v_pk_add_f32 v[32:33], v[36:37], v[32:33]
	s_nop 0
	v_mul_f32_e32 v36, 0xbfb8aa3b, v32
	v_mul_f32_e32 v37, 0xbfb8aa3b, v33
	v_exp_f32_e32 v36, v36
	v_exp_f32_e32 v37, v37
	v_pk_add_f32 v[34:35], v[38:39], v[34:35]
	v_add_f32_e32 v36, 1.0, v36
	v_add_f32_e32 v37, 1.0, v37
	v_rcp_f32_e32 v36, v36
	v_rcp_f32_e32 v37, v37
	s_nop 0
	v_pk_mul_f32 v[32:33], v[32:33], v[36:37]
	v_mul_f32_e32 v36, 0xbfb8aa3b, v34
	v_mul_f32_e32 v37, 0xbfb8aa3b, v35
	v_exp_f32_e32 v36, v36
	v_exp_f32_e32 v37, v37
	v_cvt_pk_bf16_f32 v32, v32, v33
	v_add_f32_e32 v36, 1.0, v36
	v_add_f32_e32 v37, 1.0, v37
	v_rcp_f32_e32 v36, v36
	v_rcp_f32_e32 v37, v37
	s_nop 0
	v_pk_mul_f32 v[34:35], v[34:35], v[36:37]
	s_nop 0
	v_cvt_pk_bf16_f32 v33, v34, v35
	ds_write2_b64 v48, v[50:51], v[32:33] offset0:40 offset1:42
	v_mov_b32_e32 v32, v220
	v_mov_b32_e32 v33, v221
	v_mov_b32_e32 v34, v222
	v_mov_b32_e32 v35, v223
	v_pk_add_f32 v[32:33], v[40:41], v[32:33]
	s_nop 0
	v_mul_f32_e32 v36, 0xbfb8aa3b, v32
	v_mul_f32_e32 v37, 0xbfb8aa3b, v33
	v_exp_f32_e32 v36, v36
	v_exp_f32_e32 v37, v37
	v_pk_add_f32 v[34:35], v[42:43], v[34:35]
	v_add_f32_e32 v36, 1.0, v36
	v_add_f32_e32 v37, 1.0, v37
	v_rcp_f32_e32 v36, v36
	v_rcp_f32_e32 v37, v37
	s_nop 0
	v_pk_mul_f32 v[32:33], v[32:33], v[36:37]
	v_mul_f32_e32 v36, 0xbfb8aa3b, v34
	v_mul_f32_e32 v37, 0xbfb8aa3b, v35
	v_exp_f32_e32 v36, v36
	v_exp_f32_e32 v37, v37
	v_add_f32_e32 v36, 1.0, v36
	v_add_f32_e32 v37, 1.0, v37
	v_rcp_f32_e32 v36, v36
	v_rcp_f32_e32 v37, v37
	s_nop 0
	v_pk_mul_f32 v[34:35], v[34:35], v[36:37]
	v_cvt_pk_bf16_f32 v36, v32, v33
	v_cvt_pk_bf16_f32 v37, v34, v35
	v_mov_b32_e32 v32, v224
	v_mov_b32_e32 v33, v225
	v_mov_b32_e32 v34, v226
	v_mov_b32_e32 v35, v227
	v_pk_add_f32 v[32:33], v[44:45], v[32:33]
	s_nop 0
	v_mul_f32_e32 v38, 0xbfb8aa3b, v32
	v_mul_f32_e32 v39, 0xbfb8aa3b, v33
	v_exp_f32_e32 v38, v38
	v_exp_f32_e32 v39, v39
	v_pk_add_f32 v[34:35], v[46:47], v[34:35]
	v_add_f32_e32 v38, 1.0, v38
	v_add_f32_e32 v39, 1.0, v39
	v_rcp_f32_e32 v38, v38
	v_rcp_f32_e32 v39, v39
	s_nop 0
	v_pk_mul_f32 v[32:33], v[32:33], v[38:39]
	v_mul_f32_e32 v38, 0xbfb8aa3b, v34
	v_mul_f32_e32 v39, 0xbfb8aa3b, v35
	v_exp_f32_e32 v38, v38
	v_exp_f32_e32 v39, v39
	v_cvt_pk_bf16_f32 v32, v32, v33
	v_add_f32_e32 v38, 1.0, v38
	v_add_f32_e32 v39, 1.0, v39
	v_rcp_f32_e32 v38, v38
	v_rcp_f32_e32 v39, v39
	s_nop 0
	v_pk_mul_f32 v[34:35], v[34:35], v[38:39]
	s_nop 0
	v_cvt_pk_bf16_f32 v33, v34, v35
	ds_write2_b64 v48, v[36:37], v[32:33] offset0:44 offset1:46
	v_mov_b32_e32 v32, v228
	v_mov_b32_e32 v33, v229
	v_mov_b32_e32 v34, v230
	v_mov_b32_e32 v35, v231
	v_pk_add_f32 v[16:17], v[16:17], v[32:33]
	s_nop 0
	v_mul_f32_e32 v32, 0xbfb8aa3b, v16
	v_mul_f32_e32 v33, 0xbfb8aa3b, v17
	v_exp_f32_e32 v32, v32
	v_exp_f32_e32 v33, v33
	v_pk_add_f32 v[18:19], v[18:19], v[34:35]
	v_add_f32_e32 v32, 1.0, v32
	v_add_f32_e32 v33, 1.0, v33
	v_rcp_f32_e32 v32, v32
	v_rcp_f32_e32 v33, v33
	s_nop 0
	v_pk_mul_f32 v[16:17], v[16:17], v[32:33]
	v_mul_f32_e32 v32, 0xbfb8aa3b, v18
	v_mul_f32_e32 v33, 0xbfb8aa3b, v19
	v_exp_f32_e32 v32, v32
	v_exp_f32_e32 v33, v33
	v_add_f32_e32 v32, 1.0, v32
	v_add_f32_e32 v33, 1.0, v33
	v_rcp_f32_e32 v32, v32
	v_rcp_f32_e32 v33, v33
	s_nop 0
	v_pk_mul_f32 v[18:19], v[18:19], v[32:33]
	v_cvt_pk_bf16_f32 v32, v16, v17
	v_cvt_pk_bf16_f32 v33, v18, v19
	v_mov_b32_e32 v16, v232
	v_mov_b32_e32 v17, v233
	v_mov_b32_e32 v18, v234
	v_mov_b32_e32 v19, v235
	v_pk_add_f32 v[16:17], v[20:21], v[16:17]
	s_nop 0
	v_mul_f32_e32 v20, 0xbfb8aa3b, v16
	v_mul_f32_e32 v21, 0xbfb8aa3b, v17
	v_exp_f32_e32 v20, v20
	v_exp_f32_e32 v21, v21
	v_pk_add_f32 v[18:19], v[22:23], v[18:19]
	v_add_f32_e32 v20, 1.0, v20
	v_add_f32_e32 v21, 1.0, v21
	v_rcp_f32_e32 v20, v20
	v_rcp_f32_e32 v21, v21
	s_nop 0
	v_pk_mul_f32 v[16:17], v[16:17], v[20:21]
	v_mul_f32_e32 v20, 0xbfb8aa3b, v18
	v_mul_f32_e32 v21, 0xbfb8aa3b, v19
	v_exp_f32_e32 v20, v20
	v_exp_f32_e32 v21, v21
	v_cvt_pk_bf16_f32 v16, v16, v17
	v_add_f32_e32 v20, 1.0, v20
	v_add_f32_e32 v21, 1.0, v21
	v_rcp_f32_e32 v20, v20
	v_rcp_f32_e32 v21, v21
	s_nop 0
	v_pk_mul_f32 v[18:19], v[18:19], v[20:21]
	s_nop 0
	v_cvt_pk_bf16_f32 v17, v18, v19
	ds_write2_b64 v48, v[32:33], v[16:17] offset0:48 offset1:50
	v_mov_b32_e32 v16, v236
	v_mov_b32_e32 v17, v237
	v_mov_b32_e32 v18, v238
	v_mov_b32_e32 v19, v239
	v_pk_add_f32 v[16:17], v[24:25], v[16:17]
	s_nop 0
	v_mul_f32_e32 v20, 0xbfb8aa3b, v16
	v_mul_f32_e32 v21, 0xbfb8aa3b, v17
	v_exp_f32_e32 v20, v20
	v_exp_f32_e32 v21, v21
	v_pk_add_f32 v[18:19], v[26:27], v[18:19]
	v_add_f32_e32 v20, 1.0, v20
	v_add_f32_e32 v21, 1.0, v21
	v_rcp_f32_e32 v20, v20
	v_rcp_f32_e32 v21, v21
	s_nop 0
	v_pk_mul_f32 v[16:17], v[16:17], v[20:21]
	v_mul_f32_e32 v20, 0xbfb8aa3b, v18
	v_mul_f32_e32 v21, 0xbfb8aa3b, v19
	v_exp_f32_e32 v20, v20
	v_exp_f32_e32 v21, v21
	v_add_f32_e32 v20, 1.0, v20
	v_add_f32_e32 v21, 1.0, v21
	v_rcp_f32_e32 v20, v20
	v_rcp_f32_e32 v21, v21
	s_nop 0
	v_pk_mul_f32 v[18:19], v[18:19], v[20:21]
	v_cvt_pk_bf16_f32 v20, v16, v17
	v_cvt_pk_bf16_f32 v21, v18, v19
	v_mov_b32_e32 v16, v240
	v_mov_b32_e32 v17, v241
	v_mov_b32_e32 v18, v242
	v_mov_b32_e32 v19, v243
	v_pk_add_f32 v[16:17], v[28:29], v[16:17]
	s_nop 0
	v_mul_f32_e32 v22, 0xbfb8aa3b, v16
	v_mul_f32_e32 v23, 0xbfb8aa3b, v17
	v_exp_f32_e32 v22, v22
	v_exp_f32_e32 v23, v23
; DI unsigned pack2(float a, float b) { f32x2_t v = {a, b}; bf16x2_t r = __builtin_convertvector(v, bf16x2_t); return __builtin_bit_cast(unsigned, r); }
; DI float bflo(unsigned u) { return __uint_as_float(u << 16); }
; DI float bfhi(unsigned u) { return __uint_as_float(u & 0xffff0000u); }
; DI float siluf_(float x) { return x * __builtin_amdgcn_rcpf(1.f + __expf(-x)); }
; DI void stg16_nt(void* p, u32x4 v) { __builtin_nontemporal_store(v, (u32x4*)p); }
; DI void epi_seg(const f32x16 (&acc)[4][2], const Seg& sg0, const Seg& sg1, int m0, int n0, const float* rs, const float2* cs64, const float2* cs32, bf16_t* stg) {
;     ...
; #pragma unroll
;         for (int ch = 0; ch < 2; ++ch) {
;           float ss = 0.f;
; #pragma unroll
;           for (int i = 2 * ch; i < 2 * ch + 2; ++i)
; #pragma unroll
;             for (int q4 = 0; q4 < 4; ++q4) {
;               float v[4] = {acc[i][j][4 * q4] * sc, acc[i][j][4 * q4 + 1] * sc, acc[i][j][4 * q4 + 2] * sc, acc[i][j][4 * q4 + 3] * sc};
;               if (kind == K_SILU) {
;                 const f32x4 bv = *(const f32x4*)(sg.bias + lcw + i * 32 + 8 * q4 + 4 * h);
;                 v[0] = siluf_(v[0] + bv.x); v[1] = siluf_(v[1] + bv.y); v[2] = siluf_(v[2] + bv.z); v[3] = siluf_(v[3] + bv.w);
;               }
;               const uint2 pk = make_uint2(pack2(v[0], v[1]), pack2(v[2], v[3]));
;               *(uint2*)(srow + i * 32 + 8 * q4) = pk;
;               const float f0 = bflo(pk.x), f1 = bfhi(pk.x), f2 = bflo(pk.y), f3 = bfhi(pk.y);
;               ss += (f0 * f0 + f1 * f1) + (f2 * f2 + f3 * f3);
;             }
;     ...
; #pragma unroll
;   for (int it = 0; it < 16; ++it) {
;     const int idx = tid + NTHR * it, rr = idx >> 5, c = idx & 31;
;     const Seg& fs = (c >> 4) ? sg1 : sg0;
;     const int lcc = n0 + c * 8 - fs.cbase;
;     if (fs.kind != K_NONE && lcc < fs.nvalid) {
;       const int row = m0 + rr;
;       size_t off;
;       if (fs.kind == K_KC2) { const int b = row >> 9, n = (row >> 2) & 127, g = row & 3; off = ((size_t)((b * 4 + g) * 128 + n)) * 64 + lcc; }
;       else off = (size_t)row * fs.ld + lcc;
;       stg16_nt(fs.dst + off, stage_read16(stg, rr, c));
	v_pk_add_f32 v[18:19], v[30:31], v[18:19]
	v_add_f32_e32 v22, 1.0, v22
	v_add_f32_e32 v23, 1.0, v23
	v_rcp_f32_e32 v22, v22
	v_rcp_f32_e32 v23, v23
	s_nop 0
	v_pk_mul_f32 v[16:17], v[16:17], v[22:23]
	v_mul_f32_e32 v22, 0xbfb8aa3b, v18
	v_mul_f32_e32 v23, 0xbfb8aa3b, v19
	v_exp_f32_e32 v22, v22
	v_exp_f32_e32 v23, v23
	v_cvt_pk_bf16_f32 v16, v16, v17
	v_add_f32_e32 v22, 1.0, v22
	v_add_f32_e32 v23, 1.0, v23
	v_rcp_f32_e32 v22, v22
	v_rcp_f32_e32 v23, v23
	s_nop 0
	v_pk_mul_f32 v[18:19], v[18:19], v[22:23]
	s_nop 0
	v_cvt_pk_bf16_f32 v17, v18, v19
	ds_write2_b64 v48, v[20:21], v[16:17] offset0:52 offset1:54
	v_mov_b32_e32 v16, v248
	v_mov_b32_e32 v17, v249
	v_mov_b32_e32 v18, v250
	v_mov_b32_e32 v19, v251
	v_pk_add_f32 v[0:1], v[0:1], v[16:17]
	s_nop 0
	v_mul_f32_e32 v16, 0xbfb8aa3b, v0
	v_mul_f32_e32 v17, 0xbfb8aa3b, v1
	v_exp_f32_e32 v16, v16
	v_exp_f32_e32 v17, v17
	v_pk_add_f32 v[2:3], v[2:3], v[18:19]
	v_add_f32_e32 v16, 1.0, v16
	v_add_f32_e32 v17, 1.0, v17
	v_rcp_f32_e32 v16, v16
	v_rcp_f32_e32 v17, v17
	s_nop 0
	v_pk_mul_f32 v[0:1], v[0:1], v[16:17]
	v_mul_f32_e32 v16, 0xbfb8aa3b, v2
	v_mul_f32_e32 v17, 0xbfb8aa3b, v3
	v_exp_f32_e32 v16, v16
	v_exp_f32_e32 v17, v17
	v_add_f32_e32 v16, 1.0, v16
	v_add_f32_e32 v17, 1.0, v17
	v_rcp_f32_e32 v16, v16
	v_rcp_f32_e32 v17, v17
	s_nop 0
	v_pk_mul_f32 v[2:3], v[2:3], v[16:17]
	v_cvt_pk_bf16_f32 v16, v0, v1
	v_cvt_pk_bf16_f32 v17, v2, v3
	v_mov_b32_e32 v0, v252
	v_mov_b32_e32 v1, v253
	v_mov_b32_e32 v2, v254
	v_mov_b32_e32 v3, v255
	v_pk_add_f32 v[0:1], v[4:5], v[0:1]
	s_nop 0
	v_mul_f32_e32 v4, 0xbfb8aa3b, v0
	v_mul_f32_e32 v5, 0xbfb8aa3b, v1
	v_exp_f32_e32 v4, v4
	v_exp_f32_e32 v5, v5
	v_pk_add_f32 v[2:3], v[6:7], v[2:3]
	v_add_f32_e32 v4, 1.0, v4
	v_add_f32_e32 v5, 1.0, v5
	v_rcp_f32_e32 v4, v4
	v_rcp_f32_e32 v5, v5
	s_nop 0
	v_pk_mul_f32 v[0:1], v[0:1], v[4:5]
	v_mul_f32_e32 v4, 0xbfb8aa3b, v2
	v_mul_f32_e32 v5, 0xbfb8aa3b, v3
	v_exp_f32_e32 v4, v4
	v_exp_f32_e32 v5, v5
	v_cvt_pk_bf16_f32 v0, v0, v1
	v_add_f32_e32 v4, 1.0, v4
	v_add_f32_e32 v5, 1.0, v5
	v_rcp_f32_e32 v4, v4
	v_rcp_f32_e32 v5, v5
	s_nop 0
	v_pk_mul_f32 v[2:3], v[2:3], v[4:5]
	s_nop 0
	v_cvt_pk_bf16_f32 v1, v2, v3
	ds_write2_b64 v48, v[16:17], v[0:1] offset0:56 offset1:58
	global_load_dwordx4 v[0:3], v[128:129], off offset:448
	s_waitcnt vmcnt(0)
	v_pk_add_f32 v[0:1], v[8:9], v[0:1]
	s_nop 0
	v_mul_f32_e32 v4, 0xbfb8aa3b, v0
	v_mul_f32_e32 v5, 0xbfb8aa3b, v1
	v_exp_f32_e32 v4, v4
	v_exp_f32_e32 v5, v5
	v_pk_add_f32 v[2:3], v[10:11], v[2:3]
	v_add_f32_e32 v4, 1.0, v4
	v_add_f32_e32 v5, 1.0, v5
	v_rcp_f32_e32 v4, v4
	v_rcp_f32_e32 v5, v5
	s_nop 0
	v_pk_mul_f32 v[0:1], v[0:1], v[4:5]
	v_mul_f32_e32 v4, 0xbfb8aa3b, v2
	v_mul_f32_e32 v5, 0xbfb8aa3b, v3
	v_exp_f32_e32 v4, v4
	v_exp_f32_e32 v5, v5
	v_add_f32_e32 v4, 1.0, v4
	v_add_f32_e32 v5, 1.0, v5
	v_rcp_f32_e32 v4, v4
	v_rcp_f32_e32 v5, v5
	s_nop 0
	v_pk_mul_f32 v[2:3], v[2:3], v[4:5]
	v_cvt_pk_bf16_f32 v4, v0, v1
	v_cvt_pk_bf16_f32 v5, v2, v3
	global_load_dwordx4 v[0:3], v[128:129], off offset:480
	s_waitcnt vmcnt(0)
	v_pk_add_f32 v[0:1], v[12:13], v[0:1]
	s_nop 0
	v_mul_f32_e32 v6, 0xbfb8aa3b, v0
	v_mul_f32_e32 v7, 0xbfb8aa3b, v1
	v_exp_f32_e32 v6, v6
	v_exp_f32_e32 v7, v7
	v_pk_add_f32 v[2:3], v[14:15], v[2:3]
	v_add_f32_e32 v6, 1.0, v6
	v_add_f32_e32 v7, 1.0, v7
	v_rcp_f32_e32 v6, v6
	v_rcp_f32_e32 v7, v7
	s_nop 0
	v_pk_mul_f32 v[0:1], v[0:1], v[6:7]
	v_mul_f32_e32 v6, 0xbfb8aa3b, v2
	v_mul_f32_e32 v7, 0xbfb8aa3b, v3
	v_exp_f32_e32 v6, v6
	v_exp_f32_e32 v7, v7
	v_cvt_pk_bf16_f32 v0, v0, v1
	v_add_f32_e32 v6, 1.0, v6
	v_add_f32_e32 v7, 1.0, v7
	v_rcp_f32_e32 v6, v6
	v_rcp_f32_e32 v7, v7
	s_nop 0
	v_pk_mul_f32 v[2:3], v[2:3], v[6:7]
	s_nop 0
	v_cvt_pk_bf16_f32 v1, v2, v3
	ds_write2_b64 v48, v[4:5], v[0:1] offset0:60 offset1:62
	v_lshlrev_b32_e32 v0, 4, v130
	v_ashrrev_i32_e32 v2, 5, v130
	v_and_b32_e32 v160, 0x1f0, v0
	v_add_u32_e32 v0, s34, v2
	v_ashrrev_i32_e32 v1, 31, v0
	v_lshlrev_b64 v[0:1], 9, v[0:1]
	v_lshl_add_u64 v[0:1], s[10:11], 0, v[0:1]
	v_lshl_add_u64 v[4:5], v[0:1], 0, v[160:161]
	v_mad_u64_u32 v[0:1], s[12:13], v2, s31, v[160:161]
	s_waitcnt lgkmcnt(0)
	s_barrier
; DI void stg16_nt(void* p, u32x4 v) { __builtin_nontemporal_store(v, (u32x4*)p); }
; DI void epi_seg(const f32x16 (&acc)[4][2], const Seg& sg0, const Seg& sg1, int m0, int n0, const float* rs, const float2* cs64, const float2* cs32, bf16_t* stg) {
;     ...
; #pragma unroll
;   for (int it = 0; it < 16; ++it) {
;     const int idx = tid + NTHR * it, rr = idx >> 5, c = idx & 31;
;     const Seg& fs = (c >> 4) ? sg1 : sg0;
;     const int lcc = n0 + c * 8 - fs.cbase;
;     if (fs.kind != K_NONE && lcc < fs.nvalid) {
;       const int row = m0 + rr;
;       size_t off;
;       if (fs.kind == K_KC2) { const int b = row >> 9, n = (row >> 2) & 127, g = row & 3; off = ((size_t)((b * 4 + g) * 128 + n)) * 64 + lcc; }
;       else off = (size_t)row * fs.ld + lcc;
;       stg16_nt(fs.dst + off, stage_read16(stg, rr, c));
;     }
;   }
;   __syncthreads();
	ds_read2_b64 v[0:3], v0 offset1:1
	s_waitcnt lgkmcnt(0)
	global_store_dwordx4 v[4:5], v[0:3], off nt
	s_nop 1
	v_add_u32_e32 v0, 0x200, v130
	v_ashrrev_i32_e32 v2, 5, v0
	v_add_u32_e32 v0, s34, v2
	v_ashrrev_i32_e32 v1, 31, v0
	v_lshlrev_b64 v[0:1], 9, v[0:1]
	v_lshl_add_u64 v[0:1], s[10:11], 0, v[0:1]
	v_lshl_add_u64 v[4:5], v[0:1], 0, v[160:161]
	v_mad_u64_u32 v[0:1], s[12:13], v2, s31, v[160:161]
	ds_read2_b64 v[0:3], v0 offset1:1
	s_waitcnt lgkmcnt(0)
	global_store_dwordx4 v[4:5], v[0:3], off nt
	s_nop 1
	v_add_u32_e32 v0, 0x400, v130
	v_ashrrev_i32_e32 v2, 5, v0
	v_add_u32_e32 v0, s34, v2
	v_ashrrev_i32_e32 v1, 31, v0
	v_lshlrev_b64 v[0:1], 9, v[0:1]
	v_lshl_add_u64 v[0:1], s[10:11], 0, v[0:1]
	v_lshl_add_u64 v[4:5], v[0:1], 0, v[160:161]
	v_mad_u64_u32 v[0:1], s[12:13], v2, s31, v[160:161]
	ds_read2_b64 v[0:3], v0 offset1:1
	s_waitcnt lgkmcnt(0)
	global_store_dwordx4 v[4:5], v[0:3], off nt
	s_nop 1
	v_add_u32_e32 v0, 0x600, v130
	v_ashrrev_i32_e32 v2, 5, v0
	v_add_u32_e32 v0, s34, v2
	v_ashrrev_i32_e32 v1, 31, v0
	v_lshlrev_b64 v[0:1], 9, v[0:1]
	v_lshl_add_u64 v[0:1], s[10:11], 0, v[0:1]
	v_lshl_add_u64 v[4:5], v[0:1], 0, v[160:161]
	v_mad_u64_u32 v[0:1], s[12:13], v2, s31, v[160:161]
	ds_read2_b64 v[0:3], v0 offset1:1
	s_waitcnt lgkmcnt(0)
	global_store_dwordx4 v[4:5], v[0:3], off nt
	s_nop 1
	v_add_u32_e32 v0, 0x800, v130
	v_ashrrev_i32_e32 v2, 5, v0
	v_add_u32_e32 v0, s34, v2
	v_ashrrev_i32_e32 v1, 31, v0
	v_lshlrev_b64 v[0:1], 9, v[0:1]
	v_lshl_add_u64 v[0:1], s[10:11], 0, v[0:1]
	v_lshl_add_u64 v[4:5], v[0:1], 0, v[160:161]
	v_mad_u64_u32 v[0:1], s[12:13], v2, s31, v[160:161]
	ds_read2_b64 v[0:3], v0 offset1:1
	s_waitcnt lgkmcnt(0)
	global_store_dwordx4 v[4:5], v[0:3], off nt
	s_nop 1
	v_add_u32_e32 v0, 0xa00, v130
	v_ashrrev_i32_e32 v2, 5, v0
	v_add_u32_e32 v0, s34, v2
	v_ashrrev_i32_e32 v1, 31, v0
	v_lshlrev_b64 v[0:1], 9, v[0:1]
	v_lshl_add_u64 v[0:1], s[10:11], 0, v[0:1]
	v_lshl_add_u64 v[4:5], v[0:1], 0, v[160:161]
	v_mad_u64_u32 v[0:1], s[12:13], v2, s31, v[160:161]
	ds_read2_b64 v[0:3], v0 offset1:1
	s_waitcnt lgkmcnt(0)
	global_store_dwordx4 v[4:5], v[0:3], off nt
	s_nop 1
	v_add_u32_e32 v0, 0xc00, v130
	v_ashrrev_i32_e32 v2, 5, v0
	v_add_u32_e32 v0, s34, v2
	v_ashrrev_i32_e32 v1, 31, v0
	v_lshlrev_b64 v[0:1], 9, v[0:1]
	v_lshl_add_u64 v[0:1], s[10:11], 0, v[0:1]
	v_lshl_add_u64 v[4:5], v[0:1], 0, v[160:161]
	v_mad_u64_u32 v[0:1], s[12:13], v2, s31, v[160:161]
	ds_read2_b64 v[0:3], v0 offset1:1
	s_waitcnt lgkmcnt(0)
	global_store_dwordx4 v[4:5], v[0:3], off nt
	s_nop 1
	v_add_u32_e32 v0, 0xe00, v130
	v_ashrrev_i32_e32 v2, 5, v0
	v_add_u32_e32 v0, s34, v2
	v_ashrrev_i32_e32 v1, 31, v0
	v_lshlrev_b64 v[0:1], 9, v[0:1]
	v_lshl_add_u64 v[0:1], s[10:11], 0, v[0:1]
	v_lshl_add_u64 v[4:5], v[0:1], 0, v[160:161]
	v_mad_u64_u32 v[0:1], s[12:13], v2, s31, v[160:161]
	ds_read2_b64 v[0:3], v0 offset1:1
	s_waitcnt lgkmcnt(0)
	global_store_dwordx4 v[4:5], v[0:3], off nt
	s_nop 1
	v_add_u32_e32 v0, 0x1000, v130
	v_ashrrev_i32_e32 v2, 5, v0
	v_add_u32_e32 v0, s34, v2
	v_ashrrev_i32_e32 v1, 31, v0
	v_lshlrev_b64 v[0:1], 9, v[0:1]
	v_lshl_add_u64 v[0:1], s[10:11], 0, v[0:1]
	v_lshl_add_u64 v[4:5], v[0:1], 0, v[160:161]
	v_mad_u64_u32 v[0:1], s[12:13], v2, s31, v[160:161]
	ds_read2_b64 v[0:3], v0 offset1:1
	s_waitcnt lgkmcnt(0)
	global_store_dwordx4 v[4:5], v[0:3], off nt
	s_nop 1
	v_add_u32_e32 v0, 0x1200, v130
	v_ashrrev_i32_e32 v2, 5, v0
	v_add_u32_e32 v0, s34, v2
	v_ashrrev_i32_e32 v1, 31, v0
	v_lshlrev_b64 v[0:1], 9, v[0:1]
	v_lshl_add_u64 v[0:1], s[10:11], 0, v[0:1]
	v_lshl_add_u64 v[4:5], v[0:1], 0, v[160:161]
	v_mad_u64_u32 v[0:1], s[12:13], v2, s31, v[160:161]
	ds_read2_b64 v[0:3], v0 offset1:1
	s_waitcnt lgkmcnt(0)
	global_store_dwordx4 v[4:5], v[0:3], off nt
	s_nop 1
	v_add_u32_e32 v0, 0x1400, v130
	v_ashrrev_i32_e32 v2, 5, v0
	v_add_u32_e32 v0, s34, v2
	v_ashrrev_i32_e32 v1, 31, v0
	v_lshlrev_b64 v[0:1], 9, v[0:1]
	v_lshl_add_u64 v[0:1], s[10:11], 0, v[0:1]
	v_lshl_add_u64 v[4:5], v[0:1], 0, v[160:161]
	v_mad_u64_u32 v[0:1], s[12:13], v2, s31, v[160:161]
	ds_read2_b64 v[0:3], v0 offset1:1
	s_waitcnt lgkmcnt(0)
	global_store_dwordx4 v[4:5], v[0:3], off nt
	s_nop 1
	v_add_u32_e32 v0, 0x1600, v130
	v_ashrrev_i32_e32 v2, 5, v0
	v_add_u32_e32 v0, s34, v2
	v_ashrrev_i32_e32 v1, 31, v0
	v_lshlrev_b64 v[0:1], 9, v[0:1]
	v_lshl_add_u64 v[0:1], s[10:11], 0, v[0:1]
	v_lshl_add_u64 v[4:5], v[0:1], 0, v[160:161]
	v_mad_u64_u32 v[0:1], s[12:13], v2, s31, v[160:161]
	ds_read2_b64 v[0:3], v0 offset1:1
	s_waitcnt lgkmcnt(0)
	global_store_dwordx4 v[4:5], v[0:3], off nt
	s_nop 1
	v_add_u32_e32 v0, 0x1800, v130
	v_ashrrev_i32_e32 v2, 5, v0
	v_add_u32_e32 v0, s34, v2
	v_ashrrev_i32_e32 v1, 31, v0
	v_lshlrev_b64 v[0:1], 9, v[0:1]
	v_lshl_add_u64 v[0:1], s[10:11], 0, v[0:1]
	v_lshl_add_u64 v[4:5], v[0:1], 0, v[160:161]
	v_mad_u64_u32 v[0:1], s[12:13], v2, s31, v[160:161]
	ds_read2_b64 v[0:3], v0 offset1:1
	s_waitcnt lgkmcnt(0)
	global_store_dwordx4 v[4:5], v[0:3], off nt
	s_nop 1
	v_add_u32_e32 v0, 0x1a00, v130
	v_ashrrev_i32_e32 v2, 5, v0
	v_add_u32_e32 v0, s34, v2
	v_ashrrev_i32_e32 v1, 31, v0
	v_lshlrev_b64 v[0:1], 9, v[0:1]
	v_lshl_add_u64 v[0:1], s[10:11], 0, v[0:1]
	v_lshl_add_u64 v[4:5], v[0:1], 0, v[160:161]
	v_mad_u64_u32 v[0:1], s[12:13], v2, s31, v[160:161]
	ds_read2_b64 v[0:3], v0 offset1:1
	s_waitcnt lgkmcnt(0)
	global_store_dwordx4 v[4:5], v[0:3], off nt
	s_nop 1
	v_add_u32_e32 v0, 0x1c00, v130
	v_ashrrev_i32_e32 v2, 5, v0
	v_add_u32_e32 v0, s34, v2
	v_ashrrev_i32_e32 v1, 31, v0
	v_lshlrev_b64 v[0:1], 9, v[0:1]
	v_lshl_add_u64 v[0:1], s[10:11], 0, v[0:1]
	v_lshl_add_u64 v[4:5], v[0:1], 0, v[160:161]
	v_mad_u64_u32 v[0:1], s[12:13], v2, s31, v[160:161]
	ds_read2_b64 v[0:3], v0 offset1:1
	s_waitcnt lgkmcnt(0)
	global_store_dwordx4 v[4:5], v[0:3], off nt
	s_nop 1
	v_add_u32_e32 v0, 0x1e00, v130
	v_ashrrev_i32_e32 v2, 5, v0
	v_add_u32_e32 v0, s34, v2
	v_ashrrev_i32_e32 v1, 31, v0
	v_lshlrev_b64 v[0:1], 9, v[0:1]
	v_lshl_add_u64 v[0:1], s[10:11], 0, v[0:1]
	v_lshl_add_u64 v[4:5], v[0:1], 0, v[160:161]
	v_mad_u64_u32 v[0:1], s[10:11], v2, s31, v[160:161]
	ds_read2_b64 v[0:3], v0 offset1:1
	s_waitcnt lgkmcnt(0)
	global_store_dwordx4 v[4:5], v[0:3], off nt
	s_barrier
	s_cbranch_scc1 .LBB0_1121
